# stack11 + IN epilogue row statistics and bias slice prefetched by LDS-DMA at unit top (16 KiB static LDS) instead of two exposed global round trips
# speedup vs baseline: 1.0068x; 1.0068x over previous
; template <class Epi, bool ALIGN_EPI, bool SP2, bool BF = false, bool HALFM = false, class Order = StaticOrder>
; __device__ __forceinline__ void gemm_phase(LAS unsigned char* lds, const int tid, const Gemm g, const Order& S, const Epi& E, const bool dry = false) {
;     ...
;     f32x4 acc[2][2][4][2];
; #pragma unroll
;     for (int a = 0; a < 2; ++a)
; #pragma unroll
;         for (int b = 0; b < 2; ++b)
; #pragma unroll
;             for (int m = 0; m < 4; ++m)
; #pragma unroll
;                 for (int n = 0; n < 2; ++n) acc[a][b][m][n] = (f32x4){0.f, 0.f, 0.f, 0.f};
;     __device__ __forceinline__ void operator()(const f32x4 (&acc)[2][2][4][2], const pg8::Unit& u, int wr, int wc, int fr, int fq) const {
;     ...
;         const int rloc = wr * 64 + fr;
;         const unsigned rbase = (unsigned)u.pm * 256u + (unsigned)rloc;
;         float rs[2][4];
;         { float t[2][4][4];
; #pragma unroll
;           for (int ai = 0; ai < 2; ++ai)
; #pragma unroll
;             for (int m = 0; m < 4; ++m)
; #pragma unroll
;               for (int j = 0; j < 4; ++j) t[ai][m][j] = ldg_f1(ws, (unsigned)WS_ROWSQ + ((unsigned)(4 * fq + j) * (unsigned)MROWS + rbase + ai * 128 + m * 16) * 4u);
; #pragma unroll
;           for (int ai = 0; ai < 2; ++ai)
; #pragma unroll
;             for (int m = 0; m < 4; ++m) rs[ai][m] = __builtin_amdgcn_rsqf(red4((t[ai][m][0] + t[ai][m][1]) + (t[ai][m][2] + t[ai][m][3]), fq * 16 + fr) * (1.f / 1024.f) + EPS); }
;         const bool mapA = s >= 12 && s <= 21;
;         f32x4 bv[2][2];
; #pragma unroll
;         for (int bj = 0; bj < 2; ++bj)
; #pragma unroll
;             for (int n = 0; n < 2; ++n) bv[bj][n] = ldg_f4(ws, shw_off + (unsigned)(bb * NPAD + u.pn * 256 + 128 * bj + 32 * wc + 16 * n + 4 * fq) * 4u);
.Lin_wd:
	s_mov_b32 s21, -2
	s_barrier
	v_readlane_b32 s42, v253, 0
	v_readlane_b32 s43, v253, 1
	v_readfirstlane_b32 vcc_hi, v212
	v_and_b32_e32 v132, 63, v212
	v_lshrrev_b32_e32 v133, 6, v212
	v_mul_u32_u24_e32 v133, 0x48000, v133
	v_lshlrev_b32_e32 v134, 4, v132
	v_add_u32_e32 v132, v134, v133
	s_lshl_b32 vcc_lo, s4, 10
	s_add_u32 vcc_lo, vcc_lo, 0x2880000
	v_add_u32_e32 v132, vcc_lo, v132
	s_lshl_b32 vcc_hi, vcc_hi, 5
	s_add_u32 m0, vcc_hi, 0x24000
	v_add_u32_e32 v133, 0x24000, v132
	global_load_lds_dwordx4 v132, s[42:43]
	s_add_u32 m0, vcc_hi, 0x24400
	s_nop 0
	global_load_lds_dwordx4 v133, s[42:43]
	s_cmp_lg_u32 vcc_hi, 0
	s_cbranch_scc1 .Lpf_noshw
	s_lshr_b32 vcc_lo, s4, 3
	s_cmpk_lt_u32 s4, 0x80
	s_cselect_b32 vcc_lo, vcc_lo, 16
	s_mul_i32 vcc_lo, vcc_lo, 0x3800
	s_lshl_b32 vcc_hi, s2, 10
	s_add_u32 vcc_lo, vcc_lo, vcc_hi
	s_add_u32 vcc_lo, vcc_lo, s96
	v_add_u32_e32 v134, vcc_lo, v134
	s_mov_b32 m0, 0x22400
	s_nop 0
	global_load_lds_dwordx4 v134, s[42:43]
.Lpf_noshw:
	s_cmp_lg_u32 s100, 0
	s_cbranch_scc1 .Lin_peel
	v_mov_b32_e32 v58, 0
	v_mov_b32_e32 v59, v58
	v_mov_b32_e32 v60, v58
	v_mov_b32_e32 v61, v58
	v_mov_b32_e32 v62, v58
	v_mov_b32_e32 v63, v58
	v_mov_b32_e32 v64, v58
	v_mov_b32_e32 v65, v58
	v_mov_b32_e32 v74, v58
	v_mov_b32_e32 v75, v58
	v_mov_b32_e32 v76, v58
	v_mov_b32_e32 v77, v58
	v_mov_b32_e32 v78, v58
	v_mov_b32_e32 v79, v58
	v_mov_b32_e32 v80, v58
	v_mov_b32_e32 v81, v58
	v_mov_b32_e32 v82, v58
	v_mov_b32_e32 v83, v58
	v_mov_b32_e32 v84, v58
	v_mov_b32_e32 v85, v58
	v_mov_b32_e32 v86, v58
	v_mov_b32_e32 v87, v58
	v_mov_b32_e32 v88, v58
	v_mov_b32_e32 v89, v58
	v_mov_b32_e32 v90, v58
	v_mov_b32_e32 v91, v58
	v_mov_b32_e32 v92, v58
	v_mov_b32_e32 v93, v58
	v_mov_b32_e32 v94, v58
	v_mov_b32_e32 v95, v58
	v_mov_b32_e32 v96, v58
	v_mov_b32_e32 v97, v58
	v_mov_b32_e32 v2, v58
	v_mov_b32_e32 v3, v58
	v_mov_b32_e32 v4, v58
	v_mov_b32_e32 v5, v58
	v_mov_b32_e32 v6, v58
	v_mov_b32_e32 v7, v58
	v_mov_b32_e32 v8, v58
	v_mov_b32_e32 v9, v58
	v_mov_b32_e32 v10, v58
	v_mov_b32_e32 v11, v58
	v_mov_b32_e32 v12, v58
	v_mov_b32_e32 v13, v58
	v_mov_b32_e32 v14, v58
	v_mov_b32_e32 v15, v58
	v_mov_b32_e32 v16, v58
	v_mov_b32_e32 v17, v58
	v_mov_b32_e32 v18, v58
	v_mov_b32_e32 v19, v58
	v_mov_b32_e32 v20, v58
	v_mov_b32_e32 v21, v58
	v_mov_b32_e32 v22, v58
	v_mov_b32_e32 v23, v58
	v_mov_b32_e32 v24, v58
	v_mov_b32_e32 v25, v58
	v_mov_b32_e32 v26, v58
	v_mov_b32_e32 v27, v58
	v_mov_b32_e32 v28, v58
	v_mov_b32_e32 v29, v58
	v_mov_b32_e32 v30, v58
	v_mov_b32_e32 v31, v58
	v_mov_b32_e32 v32, v58
	v_mov_b32_e32 v33, v58
	v_mov_b32_e32 v98, v58
	v_mov_b32_e32 v99, v58
	v_mov_b32_e32 v100, v58
	v_mov_b32_e32 v101, v58
	v_mov_b32_e32 v102, v58
	v_mov_b32_e32 v103, v58
	v_mov_b32_e32 v104, v58
	v_mov_b32_e32 v105, v58
	v_mov_b32_e32 v106, v58
	v_mov_b32_e32 v107, v58
	v_mov_b32_e32 v108, v58
	v_mov_b32_e32 v109, v58
	v_mov_b32_e32 v110, v58
	v_mov_b32_e32 v111, v58
	v_mov_b32_e32 v112, v58
	v_mov_b32_e32 v113, v58
	v_mov_b32_e32 v114, v58
	v_mov_b32_e32 v115, v58
	v_mov_b32_e32 v116, v58
	v_mov_b32_e32 v117, v58
	v_mov_b32_e32 v118, v58
	v_mov_b32_e32 v119, v58
	v_mov_b32_e32 v120, v58
	v_mov_b32_e32 v121, v58
	v_mov_b32_e32 v122, v58
	v_mov_b32_e32 v123, v58
	v_mov_b32_e32 v124, v58
	v_mov_b32_e32 v125, v58
	v_mov_b32_e32 v126, v58
	v_mov_b32_e32 v127, v58
	v_mov_b32_e32 v128, v58
	v_mov_b32_e32 v129, v58
	v_mov_b32_e32 v34, v58
	v_mov_b32_e32 v35, v58
	v_mov_b32_e32 v36, v58
	v_mov_b32_e32 v37, v58
	v_mov_b32_e32 v38, v58
	v_mov_b32_e32 v39, v58
	v_mov_b32_e32 v40, v58
	v_mov_b32_e32 v41, v58
	v_mov_b32_e32 v42, v58
	v_mov_b32_e32 v43, v58
	v_mov_b32_e32 v44, v58
	v_mov_b32_e32 v45, v58
	v_mov_b32_e32 v54, v58
	v_mov_b32_e32 v55, v58
	v_mov_b32_e32 v56, v58
	v_mov_b32_e32 v57, v58
	v_mov_b32_e32 v46, v58
	v_mov_b32_e32 v47, v58
	v_mov_b32_e32 v48, v58
	v_mov_b32_e32 v49, v58
	v_mov_b32_e32 v50, v58
	v_mov_b32_e32 v51, v58
	v_mov_b32_e32 v52, v58
	v_mov_b32_e32 v53, v58
	v_mov_b32_e32 v66, v58
	v_mov_b32_e32 v67, v58
	v_mov_b32_e32 v68, v58
	v_mov_b32_e32 v69, v58
	v_mov_b32_e32 v70, v58
	v_mov_b32_e32 v71, v58
	v_mov_b32_e32 v72, v58
	v_mov_b32_e32 v73, v58
